# attention H1: waves 4-7 issue their K/V LDS-DMA pieces at stages 6-10 instead of 1-5 (SIMD partners no longer block on DMA issue together); plus kv_b / out-proj epilogue rsq-load hoist
# speedup vs baseline: 1.0086x; 1.0086x over previous
; #define SBAR() __builtin_amdgcn_sched_barrier(0)
; template <int I> __device__ __forceinline__ void fs_chunk(f32x16& p0, f32x16& p1, float alpha, float& l_reg, SMState& st, bf16x8& pa0, bf16x8& pa1, bf16x8& pa2, bf16x8& pa3) {
;     ...
;   if constexpr (I < 4) {
; #pragma unroll
;     for (int r = 4 * I; r < 4 * I + 4; ++r) p1[r] = __builtin_amdgcn_exp2f(p1[r]);
;     if constexpr (I == 0) st.ps = 0.f;
;   } else if constexpr (I < 8) { constexpr int j = 4 * (I - 4);
; #pragma unroll
;     for (int r = j; r < j + 4; ++r) st.ps += p0[r];
; #pragma unroll
;     for (int r = j; r < j + 4; ++r) st.ps += p1[r];
;   } else if constexpr (I == 8) {
;     const float ps_ = st.ps;
;     auto rr = __builtin_amdgcn_permlane32_swap(__float_as_uint(ps_), __float_as_uint(ps_), false, false);
;     l_reg = l_reg * alpha + (__uint_as_float(rr[0]) + __uint_as_float(rr[1]));
;     PK4(p0, 0, pa0);
;   } else if constexpr (I == 9) { PK4(p0, 8, pa1); }
;   else if constexpr (I == 10) { PK4(p1, 0, pa2); }
;   else { PK4(p1, 8, pa3); }
;     ...
; }
; template <int P> __device__ __forceinline__ void dma_piece(const DmaCtx& c) {
;   if constexpr (P < 3) __builtin_amdgcn_raw_ptr_buffer_load_lds(c.srd, (lds_u32_t*)(c.kd + (c.wid + 8 * P) * 1024), 16, c.koff[P], c.gk, 0, 0);
;   else __builtin_amdgcn_raw_ptr_buffer_load_lds(c.srd, (lds_u32_t*)(c.vd + (c.wid + 8 * (P - 3)) * 1024), 16, c.voff[P - 3], c.gv, 0, 0);
; }
; template <int D0> __device__ __forceinline__ void h1_stage(f32x16& pc0, f32x16& pc1, f32x16& pp0, f32x16& pp1, float alP, float& l_reg, SMState& st, bf16x8& pa0, bf16x8& pa1, bf16x8& pa2, bf16x8& pa3, ...
;   bf16x8 m0, m1, mq;
;   if constexpr (D0 < 10) kq_load<D0 + 2>(m0, m1, mq, Ks, qr, qlds, kb);
;   pc0 = __builtin_amdgcn_mfma_f32_32x32x16_bf16(b0, q, pc0, 0, 0, 0);
;   pc1 = __builtin_amdgcn_mfma_f32_32x32x16_bf16(b1, q, pc1, 0, 0, 0);
;   if constexpr (D0 >= 1 && D0 <= 5) dma_piece<D0 - 1>(dc);
;   SBAR(); fs_chunk<D0>(pp0, pp1, alP, l_reg, st, pa0, pa1, pa2, pa3); SBAR();
;   if constexpr (D0 < 11) h1_stage<D0 + 1>(pc0, pc1, pp0, pp1, alP, l_reg, st, pa0, pa1, pa2, pa3, n0, n1, nq, m0, m1, mq, Ks, qr, qlds, kb, dc);
; }
.Lattn_m2:
	v_xor_b32_e32 v112, 0x80000000, v191
	v_mov_b32_e32 v113, v112
	v_mov_b32_e32 v114, v112
	v_mov_b32_e32 v115, v112
	v_mov_b32_e32 v116, v112
	v_mov_b32_e32 v117, v112
	v_mov_b32_e32 v118, v112
	v_mov_b32_e32 v119, v112
	v_mov_b32_e32 v120, v112
	v_mov_b32_e32 v121, v112
	v_mov_b32_e32 v122, v112
	v_mov_b32_e32 v123, v112
	v_mov_b32_e32 v124, v112
	v_mov_b32_e32 v125, v112
	v_mov_b32_e32 v126, v112
	v_mov_b32_e32 v127, v112
	v_add_u32_e32 v224, s10, v199
	v_add_u32_e32 v225, s10, v200
	s_waitcnt lgkmcnt(1)
	v_mfma_f32_32x32x16_bf16 v[96:111], v[204:207], v[156:159], v[112:127]
	ds_read_b128 v[204:207], v224 offset:32768
	ds_read_b128 v[212:215], v224 offset:45056
	ds_read_b128 v[216:219], v225 offset:32768
	ds_read_b128 v[220:223], v225 offset:45056
	s_mul_i32 s11, s52, 0x6000
	s_add_i32 s53, s11, 0
	s_add_i32 s11, s51, 0xfffbe000
	s_waitcnt lgkmcnt(4)
	v_mfma_f32_32x32x16_bf16 v[112:127], v[208:211], v[156:159], v[112:127]
	v_exp_f32_e32 v226, v80
	v_exp_f32_e32 v227, v81
	v_exp_f32_e32 v228, v82
	v_exp_f32_e32 v229, v83
	v_add_u32_e32 v230, s10, v201
	s_add_i32 s10, s53, s69
	s_add_i32 m0, s10, 0x8000
	ds_read_b128 v[80:83], v230 offset:32768
	ds_read_b128 v[208:211], v230 offset:45056
	s_cmp_lt_u32 s69, 0x1000
	s_cbranch_scc0 .Lattn_dAx0
	buffer_load_dwordx4 v194, s[28:31], s51 offen lds
.Lattn_dAx0:
	s_waitcnt lgkmcnt(5)
	v_mfma_f32_32x32x16_bf16 v[96:111], v[204:207], v[152:155], v[96:111]
	s_waitcnt lgkmcnt(4)
	v_mfma_f32_32x32x16_bf16 v[112:127], v[212:215], v[152:155], v[112:127]
	v_exp_f32_e32 v231, v84
	v_exp_f32_e32 v232, v85
	v_exp_f32_e32 v233, v86
	v_exp_f32_e32 v234, v87
	s_add_i32 m0, s10, 0xa000
	ds_read_b128 v[84:87], v203 offset:32896
	ds_read_b128 v[204:207], v203 offset:45184
	s_cmp_lt_u32 s69, 0x1000
	s_cbranch_scc0 .Lattn_dAx1
	buffer_load_dwordx4 v195, s[28:31], s51 offen lds
.Lattn_dAx1:
	s_waitcnt lgkmcnt(5)
	v_mfma_f32_32x32x16_bf16 v[96:111], v[216:219], v[148:151], v[96:111]
	s_waitcnt lgkmcnt(4)
	v_mfma_f32_32x32x16_bf16 v[112:127], v[220:223], v[148:151], v[112:127]
	v_exp_f32_e32 v235, v88
	v_exp_f32_e32 v236, v89
	v_exp_f32_e32 v237, v90
	v_exp_f32_e32 v238, v91
	s_add_i32 m0, s10, 0xc000
	ds_read_b128 v[88:91], v224 offset:32896
	ds_read_b128 v[212:215], v224 offset:45184
	s_cmp_lt_u32 s69, 0x1000
	s_cbranch_scc0 .Lattn_dAx2
	buffer_load_dwordx4 v196, s[28:31], s51 offen lds
.Lattn_dAx2:
	s_waitcnt lgkmcnt(5)
	v_mfma_f32_32x32x16_bf16 v[96:111], v[80:83], v[144:147], v[96:111]
	s_waitcnt lgkmcnt(4)
	v_mfma_f32_32x32x16_bf16 v[112:127], v[208:211], v[144:147], v[112:127]
	v_exp_f32_e32 v239, v92
	v_exp_f32_e32 v240, v93
	v_exp_f32_e32 v241, v94
	v_exp_f32_e32 v242, v95
	s_mov_b32 m0, s50
	ds_read_b128 v[80:83], v225 offset:32896
	ds_read_b128 v[92:95], v225 offset:45184
	s_cmp_lt_u32 s69, 0x1000
	s_cbranch_scc0 .Lattn_dAx3
	buffer_load_dwordx4 v197, s[28:31], s11 offen lds
.Lattn_dAx3:
	s_waitcnt lgkmcnt(5)
	v_mfma_f32_32x32x16_bf16 v[96:111], v[84:87], v[140:143], v[96:111]
	s_waitcnt lgkmcnt(4)
	v_mfma_f32_32x32x16_bf16 v[112:127], v[204:207], v[140:143], v[112:127]
	v_add_f32_e32 v84, 0, v64
	v_add_f32_e32 v84, v65, v84
	v_add_f32_e32 v84, v66, v84
	v_add_f32_e32 v84, v67, v84
	v_add_f32_e32 v84, v226, v84
	v_add_f32_e32 v84, v227, v84
	v_add_f32_e32 v84, v228, v84
	v_add_f32_e32 v208, v229, v84
	s_mov_b32 m0, s49
	ds_read_b128 v[84:87], v230 offset:32896
	ds_read_b128 v[204:207], v230 offset:45184
	s_cmp_lt_u32 s69, 0x1000
	s_cbranch_scc0 .Lattn_dAx4
	buffer_load_dwordx4 v198, s[28:31], s11 offen lds
.Lattn_dAx4:
	s_waitcnt lgkmcnt(5)
	v_mfma_f32_32x32x16_bf16 v[96:111], v[88:91], v[136:139], v[96:111]
	s_waitcnt lgkmcnt(4)
	v_mfma_f32_32x32x16_bf16 v[112:127], v[212:215], v[136:139], v[112:127]
	v_add_f32_e32 v88, v68, v208
	v_add_f32_e32 v88, v69, v88
	v_add_f32_e32 v88, v70, v88
	v_add_f32_e32 v88, v71, v88
	v_add_f32_e32 v88, v231, v88
	v_add_f32_e32 v88, v232, v88
	v_add_f32_e32 v88, v233, v88
	v_add_f32_e32 v212, v234, v88
	s_cmp_lt_u32 s69, 0x1000
	s_cbranch_scc1 .Lattn_dBx0
	s_add_i32 m0, s10, 0x8000
	s_nop 0
	buffer_load_dwordx4 v194, s[28:31], s51 offen lds
.Lattn_dBx0:
	s_waitcnt lgkmcnt(3)
	v_mfma_f32_32x32x16_bf16 v[96:111], v[80:83], v[132:135], v[96:111]
	ds_read_b128 v[80:83], v203 offset:45312
	ds_read_b128 v[88:91], v203 offset:33024
	ds_read_b128 v[208:211], v192
	s_waitcnt lgkmcnt(5)
	v_mfma_f32_32x32x16_bf16 v[112:127], v[92:95], v[132:135], v[112:127]
	v_add_f32_e32 v92, v72, v212
	v_add_f32_e32 v92, v73, v92
	v_add_f32_e32 v92, v74, v92
	v_add_f32_e32 v92, v75, v92
	v_add_f32_e32 v92, v235, v92
	v_add_f32_e32 v92, v236, v92
	v_add_f32_e32 v92, v237, v92
	v_add_f32_e32 v203, v238, v92
	s_cmp_lt_u32 s69, 0x1000
	s_cbranch_scc1 .Lattn_dBx1
	s_add_i32 m0, s10, 0xa000
	s_nop 0
	buffer_load_dwordx4 v195, s[28:31], s51 offen lds
; #define SBAR() __builtin_amdgcn_sched_barrier(0)
; template <int I> __device__ __forceinline__ void fs_chunk(f32x16& p0, f32x16& p1, float alpha, float& l_reg, SMState& st, bf16x8& pa0, bf16x8& pa1, bf16x8& pa2, bf16x8& pa3) {
;     ...
;   if constexpr (I < 4) {
; #pragma unroll
;     for (int r = 4 * I; r < 4 * I + 4; ++r) p1[r] = __builtin_amdgcn_exp2f(p1[r]);
;     if constexpr (I == 0) st.ps = 0.f;
;   } else if constexpr (I < 8) { constexpr int j = 4 * (I - 4);
; #pragma unroll
;     for (int r = j; r < j + 4; ++r) st.ps += p0[r];
; #pragma unroll
;     for (int r = j; r < j + 4; ++r) st.ps += p1[r];
;   } else if constexpr (I == 8) {
;     const float ps_ = st.ps;
;     auto rr = __builtin_amdgcn_permlane32_swap(__float_as_uint(ps_), __float_as_uint(ps_), false, false);
;     l_reg = l_reg * alpha + (__uint_as_float(rr[0]) + __uint_as_float(rr[1]));
;     PK4(p0, 0, pa0);
;   } else if constexpr (I == 9) { PK4(p0, 8, pa1); }
;   else if constexpr (I == 10) { PK4(p1, 0, pa2); }
;   else { PK4(p1, 8, pa3); }
;     ...
; }
; template <int D0> __device__ __forceinline__ void h1_stage(f32x16& pc0, f32x16& pc1, f32x16& pp0, f32x16& pp1, float alP, float& l_reg, SMState& st, bf16x8& pa0, bf16x8& pa1, bf16x8& pa2, bf16x8& pa3, ...
;   bf16x8 m0, m1, mq;
;   if constexpr (D0 < 10) kq_load<D0 + 2>(m0, m1, mq, Ks, qr, qlds, kb);
;   pc0 = __builtin_amdgcn_mfma_f32_32x32x16_bf16(b0, q, pc0, 0, 0, 0);
;   pc1 = __builtin_amdgcn_mfma_f32_32x32x16_bf16(b1, q, pc1, 0, 0, 0);
;   if constexpr (D0 >= 1 && D0 <= 5) dma_piece<D0 - 1>(dc);
;   SBAR(); fs_chunk<D0>(pp0, pp1, alP, l_reg, st, pa0, pa1, pa2, pa3); SBAR();
;   if constexpr (D0 < 11) h1_stage<D0 + 1>(pc0, pc1, pp0, pp1, alP, l_reg, st, pa0, pa1, pa2, pa3, n0, n1, nq, m0, m1, mq, Ks, qr, qlds, kb, dc);
; }
; template <int G> __device__ __forceinline__ void v_load(s16x4& la, s16x4& ha, s16x4& lb, s16x4& hb, const __attribute__((address_space(3))) char* vb) {
;   constexpr int ks = G >> 1, d0 = (G & 1) * 2;
;   la = __builtin_amdgcn_ds_read_tr16_b64_v4i16((lds_s16x4b*)(vb + v_rd_off(d0, ks, 0))); ha = __builtin_amdgcn_ds_read_tr16_b64_v4i16((lds_s16x4b*)(vb + v_rd_off(d0, ks, 1)));
;   lb = __builtin_amdgcn_ds_read_tr16_b64_v4i16((lds_s16x4b*)(vb + v_rd_off(d0 + 1, ks, 0))); hb = __builtin_amdgcn_ds_read_tr16_b64_v4i16((lds_s16x4b*)(vb + v_rd_off(d0 + 1, ks, 1)));
; }
.Lattn_dBx1:
	s_waitcnt lgkmcnt(4)
	v_mfma_f32_32x32x16_bf16 v[96:111], v[84:87], v[128:131], v[96:111]
	ds_read_b128 v[84:87], v224 offset:45312
	ds_read_b128 v[92:95], v224 offset:33024
	ds_read_b128 v[212:215], v192 offset:1024
	s_waitcnt lgkmcnt(6)
	v_mfma_f32_32x32x16_bf16 v[112:127], v[204:207], v[128:131], v[112:127]
	v_add_f32_e32 v203, v76, v203
	v_add_f32_e32 v203, v77, v203
	v_add_f32_e32 v203, v78, v203
	v_add_f32_e32 v203, v79, v203
	v_add_f32_e32 v203, v239, v203
	v_add_f32_e32 v203, v240, v203
	v_add_f32_e32 v203, v241, v203
	v_add_f32_e32 v203, v242, v203
	s_cmp_lt_u32 s69, 0x1000
	s_cbranch_scc1 .Lattn_dBx2
	s_add_i32 m0, s10, 0xc000
	s_nop 0
	buffer_load_dwordx4 v196, s[28:31], s51 offen lds
.Lattn_dBx2:
	s_waitcnt lgkmcnt(3)
	v_mfma_f32_32x32x16_bf16 v[96:111], v[88:91], v[208:211], v[96:111]
	ds_read_b128 v[88:91], v225 offset:45312
	ds_read_b128 v[216:219], v225 offset:33024
	ds_read_b128 v[220:223], v192 offset:2048
	v_mfma_f32_32x32x16_bf16 v[112:127], v[80:83], v[208:211], v[112:127]
	v_mov_b32_e32 v204, v203
	v_cvt_pk_bf16_f32 v80, v64, v65
	v_cvt_pk_bf16_f32 v81, v66, v67
	v_cvt_pk_bf16_f32 v82, v68, v69
	v_cvt_pk_bf16_f32 v83, v70, v71
	v_permlane32_swap_b32_e32 v203, v204
	v_permlane32_swap_b32_e32 v80, v82
	v_permlane32_swap_b32_e32 v81, v83
	s_cmp_lt_u32 s69, 0x1000
	s_cbranch_scc1 .Lattn_dBx3
	s_mov_b32 m0, s50
	s_nop 0
	buffer_load_dwordx4 v197, s[28:31], s11 offen lds
.Lattn_dBx3:
	s_waitcnt lgkmcnt(3)
	v_mfma_f32_32x32x16_bf16 v[96:111], v[92:95], v[212:215], v[96:111]
	ds_read_b128 v[64:67], v192 offset:3072
	ds_read_b128 v[92:95], v230 offset:33024
	ds_read_b128 v[206:209], v230 offset:45312
	v_mfma_f32_32x32x16_bf16 v[112:127], v[84:87], v[212:215], v[112:127]
	v_cvt_pk_bf16_f32 v72, v72, v73
	v_cvt_pk_bf16_f32 v73, v74, v75
	v_cvt_pk_bf16_f32 v74, v76, v77
	v_cvt_pk_bf16_f32 v75, v78, v79
	s_nop 0
	v_permlane32_swap_b32_e32 v72, v74
	v_permlane32_swap_b32_e32 v73, v75
	s_cmp_lt_u32 s69, 0x1000
	s_cbranch_scc1 .Lattn_dBx4
	s_mov_b32 m0, s49
	s_nop 0
	buffer_load_dwordx4 v198, s[28:31], s11 offen lds
.Lattn_dBx4:
	s_waitcnt lgkmcnt(3)
	v_mfma_f32_32x32x16_bf16 v[96:111], v[216:219], v[220:223], v[96:111]
	v_mfma_f32_32x32x16_bf16 v[112:127], v[88:91], v[220:223], v[112:127]
	v_cvt_pk_bf16_f32 v68, v226, v227
	v_cvt_pk_bf16_f32 v69, v228, v229
	v_cvt_pk_bf16_f32 v70, v231, v232
	v_cvt_pk_bf16_f32 v71, v233, v234
	s_nop 0
	v_permlane32_swap_b32_e32 v68, v70
	v_permlane32_swap_b32_e32 v69, v71
	s_waitcnt lgkmcnt(1)
	v_mfma_f32_32x32x16_bf16 v[96:111], v[92:95], v[64:67], v[96:111]
	s_waitcnt lgkmcnt(0)
	v_mfma_f32_32x32x16_bf16 v[112:127], v[206:209], v[64:67], v[112:127]
	v_cvt_pk_bf16_f32 v64, v235, v236
	v_cvt_pk_bf16_f32 v65, v237, v238
	v_cvt_pk_bf16_f32 v66, v239, v240
	v_cvt_pk_bf16_f32 v67, v241, v242
	s_nop 0
	v_permlane32_swap_b32_e32 v64, v66
	v_permlane32_swap_b32_e32 v65, v67
	ds_read_b64_tr_b16 v[78:79], v188 offset:2048
	ds_read_b64_tr_b16 v[76:77], v188
	ds_read_b64_tr_b16 v[84:85], v188 offset:512
	ds_read_b64_tr_b16 v[88:89], v188 offset:1024
	ds_read_b64_tr_b16 v[92:93], v188 offset:1536
	ds_read_b64_tr_b16 v[86:87], v188 offset:2560
	ds_read_b64_tr_b16 v[90:91], v188 offset:3072
	ds_read_b64_tr_b16 v[94:95], v188 offset:3584
	s_waitcnt lgkmcnt(6)
	v_mfma_f32_32x32x16_bf16 v[0:15], v[80:83], v[76:79], v[0:15]
	s_waitcnt lgkmcnt(2)
	v_mfma_f32_32x32x16_bf16 v[48:63], v[80:83], v[84:87], v[48:63]
	v_max_f32_e32 v76, v97, v97
	v_max_f32_e32 v77, v96, v96
	v_max_f32_e32 v76, v77, v76
	v_max3_f32 v76, v76, v98, v99
	v_max3_f32 v76, v76, v100, v101
	v_max3_f32 v76, v76, v102, v103
	v_max3_f32 v76, v76, v104, v105
	v_max3_f32 v76, v76, v106, v107
	v_max3_f32 v76, v76, v108, v109
	v_max3_f32 v84, v76, v110, v111
	s_waitcnt lgkmcnt(1)
	v_mfma_f32_32x32x16_bf16 v[32:47], v[80:83], v[88:91], v[32:47]
	ds_read_b64_tr_b16 v[76:77], v188 offset:4096
	ds_read_b64_tr_b16 v[78:79], v188 offset:6144
	ds_read_b64_tr_b16 v[88:89], v188 offset:6656
	ds_read_b64_tr_b16 v[86:87], v188 offset:4608
	s_waitcnt lgkmcnt(4)
	v_mfma_f32_32x32x16_bf16 v[16:31], v[80:83], v[92:95], v[16:31]
	v_max3_f32 v80, v84, v112, v113
	v_max3_f32 v80, v80, v114, v115
	v_max3_f32 v80, v80, v116, v117
	v_max3_f32 v80, v80, v118, v119
	v_max3_f32 v80, v80, v120, v121
	v_max3_f32 v80, v80, v122, v123
	v_max3_f32 v80, v80, v124, v125
	v_max3_f32 v80, v80, v126, v127
	v_mov_b32_e32 v81, v80
	s_nop 1
	v_permlane32_swap_b32_e32 v80, v81
	v_max_f32_e32 v81, v81, v81
	v_max_f32_e32 v80, v80, v80
	v_max_f32_e32 v84, v80, v81
	s_waitcnt lgkmcnt(2)
	v_mfma_f32_32x32x16_bf16 v[0:15], v[72:75], v[76:79], v[0:15]
	ds_read_b64_tr_b16 v[80:81], v188 offset:5120
	ds_read_b64_tr_b16 v[82:83], v188 offset:7168
	ds_read_b64_tr_b16 v[78:79], v188 offset:7680
	ds_read_b64_tr_b16 v[76:77], v188 offset:5632
	s_waitcnt lgkmcnt(4)
	v_mfma_f32_32x32x16_bf16 v[48:63], v[72:75], v[86:89], v[48:63]
	v_cmp_ge_f32_e32 vcc, s67, v84
	s_cmp_eq_u64 vcc, exec
	s_cbranch_scc0 .LBB0_668
	v_mov_b32_e32 v206, 1.0

; #define SBAR() __builtin_amdgcn_sched_barrier(0)
; template <int I> __device__ __forceinline__ void fs_chunk(f32x16& p0, f32x16& p1, float alpha, float& l_reg, SMState& st, bf16x8& pa0, bf16x8& pa1, bf16x8& pa2, bf16x8& pa3) {
;     ...
;   if constexpr (I < 4) {
; #pragma unroll
;     for (int r = 4 * I; r < 4 * I + 4; ++r) p1[r] = __builtin_amdgcn_exp2f(p1[r]);
;     if constexpr (I == 0) st.ps = 0.f;
;   } else if constexpr (I < 8) { constexpr int j = 4 * (I - 4);
; #pragma unroll
;     for (int r = j; r < j + 4; ++r) st.ps += p0[r];
; #pragma unroll
;     for (int r = j; r < j + 4; ++r) st.ps += p1[r];
;   } else if constexpr (I == 8) {
;     const float ps_ = st.ps;
;     auto rr = __builtin_amdgcn_permlane32_swap(__float_as_uint(ps_), __float_as_uint(ps_), false, false);
;     l_reg = l_reg * alpha + (__uint_as_float(rr[0]) + __uint_as_float(rr[1]));
;     PK4(p0, 0, pa0);
;   } else if constexpr (I == 9) { PK4(p0, 8, pa1); }
;   else if constexpr (I == 10) { PK4(p1, 0, pa2); }
;   else { PK4(p1, 8, pa3); }
;     ...
; }
; template <int P> __device__ __forceinline__ void dma_piece(const DmaCtx& c) {
;   if constexpr (P < 3) __builtin_amdgcn_raw_ptr_buffer_load_lds(c.srd, (lds_u32_t*)(c.kd + (c.wid + 8 * P) * 1024), 16, c.koff[P], c.gk, 0, 0);
;   else __builtin_amdgcn_raw_ptr_buffer_load_lds(c.srd, (lds_u32_t*)(c.vd + (c.wid + 8 * (P - 3)) * 1024), 16, c.voff[P - 3], c.gv, 0, 0);
; }
; template <int D0> __device__ __forceinline__ void h1_stage(f32x16& pc0, f32x16& pc1, f32x16& pp0, f32x16& pp1, float alP, float& l_reg, SMState& st, bf16x8& pa0, bf16x8& pa1, bf16x8& pa2, bf16x8& pa3, ...
;   bf16x8 m0, m1, mq;
;   if constexpr (D0 < 10) kq_load<D0 + 2>(m0, m1, mq, Ks, qr, qlds, kb);
;   pc0 = __builtin_amdgcn_mfma_f32_32x32x16_bf16(b0, q, pc0, 0, 0, 0);
;   pc1 = __builtin_amdgcn_mfma_f32_32x32x16_bf16(b1, q, pc1, 0, 0, 0);
;   if constexpr (D0 >= 1 && D0 <= 5) dma_piece<D0 - 1>(dc);
;   SBAR(); fs_chunk<D0>(pp0, pp1, alP, l_reg, st, pa0, pa1, pa2, pa3); SBAR();
;   if constexpr (D0 < 11) h1_stage<D0 + 1>(pc0, pc1, pp0, pp1, alP, l_reg, st, pa0, pa1, pa2, pa3, n0, n1, nq, m0, m1, mq, Ks, qr, qlds, kb, dc);
; }
.Lattn_m1:
	v_xor_b32_e32 v80, 0x80000000, v191
	v_mov_b32_e32 v81, v80
	v_mov_b32_e32 v82, v80
	v_mov_b32_e32 v83, v80
	v_mov_b32_e32 v84, v80
	v_mov_b32_e32 v85, v80
	v_mov_b32_e32 v86, v80
	v_mov_b32_e32 v87, v80
	v_mov_b32_e32 v88, v80
	v_mov_b32_e32 v89, v80
	v_mov_b32_e32 v90, v80
	v_mov_b32_e32 v91, v80
	v_mov_b32_e32 v92, v80
	v_mov_b32_e32 v93, v80
	v_mov_b32_e32 v94, v80
	v_mov_b32_e32 v95, v80
	v_add_u32_e32 v207, s53, v199
	v_add_u32_e32 v228, s53, v200
	s_waitcnt lgkmcnt(1)
	v_mfma_f32_32x32x16_bf16 v[64:79], v[208:211], v[156:159], v[80:95]
	s_add_i32 s10, s51, 0x42000
	s_add_i32 s11, s52, 1
	ds_read_b128 v[208:211], v207 offset:32768
	ds_read_b128 v[216:219], v207 offset:45056
	ds_read_b128 v[220:223], v228 offset:32768
	ds_read_b128 v[224:227], v228 offset:45056
	s_cmp_lg_u32 s52, 2
	s_cselect_b32 s73, s11, 0
	s_mul_i32 s11, s73, 0x6000
	s_waitcnt lgkmcnt(4)
	v_mfma_f32_32x32x16_bf16 v[80:95], v[212:215], v[156:159], v[80:95]
	s_add_i32 s52, s11, 0
	v_exp_f32_e32 v229, v112
	v_exp_f32_e32 v230, v113
	v_exp_f32_e32 v231, v114
	v_exp_f32_e32 v232, v115
	s_add_i32 s11, s52, s69
	v_add_u32_e32 v233, s53, v201
	s_add_i32 m0, s11, 0x8000
	ds_read_b128 v[112:115], v233 offset:32768
	ds_read_b128 v[212:215], v233 offset:45056
	s_cmp_lt_u32 s69, 0x1000
	s_cbranch_scc0 .Lattn_dAy0
	buffer_load_dwordx4 v194, s[28:31], s10 offen lds
.Lattn_dAy0:
	s_waitcnt lgkmcnt(5)
	v_mfma_f32_32x32x16_bf16 v[64:79], v[208:211], v[152:155], v[64:79]
	s_waitcnt lgkmcnt(4)
	v_mfma_f32_32x32x16_bf16 v[80:95], v[216:219], v[152:155], v[80:95]
	v_exp_f32_e32 v234, v116
	v_exp_f32_e32 v235, v117
	v_exp_f32_e32 v236, v118
	v_exp_f32_e32 v237, v119
	s_add_i32 m0, s11, 0xa000
	ds_read_b128 v[116:119], v205 offset:32896
	ds_read_b128 v[208:211], v205 offset:45184
	s_cmp_lt_u32 s69, 0x1000
	s_cbranch_scc0 .Lattn_dAy1
	buffer_load_dwordx4 v195, s[28:31], s10 offen lds
.Lattn_dAy1:
	s_waitcnt lgkmcnt(5)
	v_mfma_f32_32x32x16_bf16 v[64:79], v[220:223], v[148:151], v[64:79]
	s_waitcnt lgkmcnt(4)
	v_mfma_f32_32x32x16_bf16 v[80:95], v[224:227], v[148:151], v[80:95]
	v_exp_f32_e32 v238, v120
	v_exp_f32_e32 v239, v121
	v_exp_f32_e32 v240, v122
	v_exp_f32_e32 v241, v123
	s_add_i32 m0, s11, 0xc000
	ds_read_b128 v[120:123], v207 offset:32896
	ds_read_b128 v[216:219], v207 offset:45184
	s_cmp_lt_u32 s69, 0x1000
	s_cbranch_scc0 .Lattn_dAy2
	buffer_load_dwordx4 v196, s[28:31], s10 offen lds
.Lattn_dAy2:
	s_waitcnt lgkmcnt(5)
	v_mfma_f32_32x32x16_bf16 v[64:79], v[112:115], v[144:147], v[64:79]
	s_waitcnt lgkmcnt(4)
	v_mfma_f32_32x32x16_bf16 v[80:95], v[212:215], v[144:147], v[80:95]
	v_exp_f32_e32 v242, v124
	v_exp_f32_e32 v243, v125
	v_exp_f32_e32 v244, v126
	v_exp_f32_e32 v245, v127
	s_mov_b32 m0, s70
	ds_read_b128 v[112:115], v228 offset:32896
	ds_read_b128 v[124:127], v228 offset:45184
	s_cmp_lt_u32 s69, 0x1000
	s_cbranch_scc0 .Lattn_dAy3
	buffer_load_dwordx4 v197, s[28:31], s51 offen lds
.Lattn_dAy3:
	s_waitcnt lgkmcnt(5)
	v_mfma_f32_32x32x16_bf16 v[64:79], v[116:119], v[140:143], v[64:79]
	s_waitcnt lgkmcnt(4)
	v_mfma_f32_32x32x16_bf16 v[80:95], v[208:211], v[140:143], v[80:95]
	v_add_f32_e32 v116, 0, v96
	v_add_f32_e32 v116, v97, v116
	v_add_f32_e32 v116, v98, v116
	v_add_f32_e32 v116, v99, v116
	v_add_f32_e32 v116, v229, v116
	v_add_f32_e32 v116, v230, v116
	v_add_f32_e32 v116, v231, v116
	v_add_f32_e32 v212, v232, v116
	s_mov_b32 m0, s71
	ds_read_b128 v[116:119], v233 offset:32896
	ds_read_b128 v[208:211], v233 offset:45184
	s_cmp_lt_u32 s69, 0x1000
	s_cbranch_scc0 .Lattn_dAy4
	buffer_load_dwordx4 v198, s[28:31], s51 offen lds
.Lattn_dAy4:
	s_waitcnt lgkmcnt(5)
	v_mfma_f32_32x32x16_bf16 v[64:79], v[120:123], v[136:139], v[64:79]
	s_waitcnt lgkmcnt(4)
	v_mfma_f32_32x32x16_bf16 v[80:95], v[216:219], v[136:139], v[80:95]
	v_add_f32_e32 v120, v100, v212
	v_add_f32_e32 v120, v101, v120
	v_add_f32_e32 v120, v102, v120
	v_add_f32_e32 v120, v103, v120
	v_add_f32_e32 v120, v234, v120
	v_add_f32_e32 v120, v235, v120
	v_add_f32_e32 v120, v236, v120
	v_add_f32_e32 v216, v237, v120
	s_cmp_lt_u32 s69, 0x1000
	s_cbranch_scc1 .Lattn_dBy0
	s_add_i32 m0, s11, 0x8000
	s_nop 0
	buffer_load_dwordx4 v194, s[28:31], s10 offen lds
.Lattn_dBy0:
	s_waitcnt lgkmcnt(3)
	v_mfma_f32_32x32x16_bf16 v[64:79], v[112:115], v[132:135], v[64:79]
	ds_read_b128 v[112:115], v205 offset:45312
	ds_read_b128 v[120:123], v205 offset:33024
	ds_read_b128 v[212:215], v192
	s_waitcnt lgkmcnt(5)
	v_mfma_f32_32x32x16_bf16 v[80:95], v[124:127], v[132:135], v[80:95]
	v_add_f32_e32 v124, v104, v216
	v_add_f32_e32 v124, v105, v124
	v_add_f32_e32 v124, v106, v124
	v_add_f32_e32 v124, v107, v124
	v_add_f32_e32 v124, v238, v124
	v_add_f32_e32 v124, v239, v124
	v_add_f32_e32 v124, v240, v124
	v_add_f32_e32 v205, v241, v124
	s_cmp_lt_u32 s69, 0x1000
	s_cbranch_scc1 .Lattn_dBy1
	s_add_i32 m0, s11, 0xa000
	s_nop 0
	buffer_load_dwordx4 v195, s[28:31], s10 offen lds
; #define SBAR() __builtin_amdgcn_sched_barrier(0)
; template <int I> __device__ __forceinline__ void fs_chunk(f32x16& p0, f32x16& p1, float alpha, float& l_reg, SMState& st, bf16x8& pa0, bf16x8& pa1, bf16x8& pa2, bf16x8& pa3) {
;     ...
;   if constexpr (I < 4) {
; #pragma unroll
;     for (int r = 4 * I; r < 4 * I + 4; ++r) p1[r] = __builtin_amdgcn_exp2f(p1[r]);
;     if constexpr (I == 0) st.ps = 0.f;
;   } else if constexpr (I < 8) { constexpr int j = 4 * (I - 4);
; #pragma unroll
;     for (int r = j; r < j + 4; ++r) st.ps += p0[r];
; #pragma unroll
;     for (int r = j; r < j + 4; ++r) st.ps += p1[r];
;   } else if constexpr (I == 8) {
;     const float ps_ = st.ps;
;     auto rr = __builtin_amdgcn_permlane32_swap(__float_as_uint(ps_), __float_as_uint(ps_), false, false);
;     l_reg = l_reg * alpha + (__uint_as_float(rr[0]) + __uint_as_float(rr[1]));
;     PK4(p0, 0, pa0);
;   } else if constexpr (I == 9) { PK4(p0, 8, pa1); }
;   else if constexpr (I == 10) { PK4(p1, 0, pa2); }
;   else { PK4(p1, 8, pa3); }
;     ...
; }
; template <int D0> __device__ __forceinline__ void h1_stage(f32x16& pc0, f32x16& pc1, f32x16& pp0, f32x16& pp1, float alP, float& l_reg, SMState& st, bf16x8& pa0, bf16x8& pa1, bf16x8& pa2, bf16x8& pa3, ...
;   bf16x8 m0, m1, mq;
;   if constexpr (D0 < 10) kq_load<D0 + 2>(m0, m1, mq, Ks, qr, qlds, kb);
;   pc0 = __builtin_amdgcn_mfma_f32_32x32x16_bf16(b0, q, pc0, 0, 0, 0);
;   pc1 = __builtin_amdgcn_mfma_f32_32x32x16_bf16(b1, q, pc1, 0, 0, 0);
;   if constexpr (D0 >= 1 && D0 <= 5) dma_piece<D0 - 1>(dc);
;   SBAR(); fs_chunk<D0>(pp0, pp1, alP, l_reg, st, pa0, pa1, pa2, pa3); SBAR();
;   if constexpr (D0 < 11) h1_stage<D0 + 1>(pc0, pc1, pp0, pp1, alP, l_reg, st, pa0, pa1, pa2, pa3, n0, n1, nq, m0, m1, mq, Ks, qr, qlds, kb, dc);
; }
; template <int G> __device__ __forceinline__ void v_load(s16x4& la, s16x4& ha, s16x4& lb, s16x4& hb, const __attribute__((address_space(3))) char* vb) {
;   constexpr int ks = G >> 1, d0 = (G & 1) * 2;
;   la = __builtin_amdgcn_ds_read_tr16_b64_v4i16((lds_s16x4b*)(vb + v_rd_off(d0, ks, 0))); ha = __builtin_amdgcn_ds_read_tr16_b64_v4i16((lds_s16x4b*)(vb + v_rd_off(d0, ks, 1)));
;   lb = __builtin_amdgcn_ds_read_tr16_b64_v4i16((lds_s16x4b*)(vb + v_rd_off(d0 + 1, ks, 0))); hb = __builtin_amdgcn_ds_read_tr16_b64_v4i16((lds_s16x4b*)(vb + v_rd_off(d0 + 1, ks, 1)));
; }
.Lattn_dBy1:
	s_waitcnt lgkmcnt(4)
	v_mfma_f32_32x32x16_bf16 v[64:79], v[116:119], v[128:131], v[64:79]
	ds_read_b128 v[124:127], v207 offset:45312
	ds_read_b128 v[216:219], v207 offset:33024
	ds_read_b128 v[220:223], v192 offset:1024
	s_waitcnt lgkmcnt(6)
	v_mfma_f32_32x32x16_bf16 v[80:95], v[208:211], v[128:131], v[80:95]
	v_add_f32_e32 v116, v108, v205
	v_add_f32_e32 v116, v109, v116
	v_add_f32_e32 v116, v110, v116
	v_add_f32_e32 v116, v111, v116
	v_add_f32_e32 v116, v242, v116
	v_add_f32_e32 v116, v243, v116
	v_add_f32_e32 v116, v244, v116
	v_add_f32_e32 v116, v245, v116
	s_cmp_lt_u32 s69, 0x1000
	s_cbranch_scc1 .Lattn_dBy2
	s_add_i32 m0, s11, 0xc000
	s_nop 0
	buffer_load_dwordx4 v196, s[28:31], s10 offen lds
.Lattn_dBy2:
	s_waitcnt lgkmcnt(3)
	v_mfma_f32_32x32x16_bf16 v[64:79], v[120:123], v[212:215], v[64:79]
	ds_read_b128 v[118:121], v228 offset:45312
	ds_read_b128 v[208:211], v228 offset:33024
	ds_read_b128 v[224:227], v192 offset:2048
	v_mfma_f32_32x32x16_bf16 v[80:95], v[112:115], v[212:215], v[80:95]
	v_mov_b32_e32 v117, v116
	v_cvt_pk_bf16_f32 v112, v96, v97
	v_cvt_pk_bf16_f32 v113, v98, v99
	v_cvt_pk_bf16_f32 v114, v100, v101
	v_cvt_pk_bf16_f32 v115, v102, v103
	v_permlane32_swap_b32_e32 v116, v117
	v_permlane32_swap_b32_e32 v112, v114
	v_permlane32_swap_b32_e32 v113, v115
	s_cmp_lt_u32 s69, 0x1000
	s_cbranch_scc1 .Lattn_dBy3
	s_mov_b32 m0, s70
	s_nop 0
	buffer_load_dwordx4 v197, s[28:31], s51 offen lds
.Lattn_dBy3:
	s_waitcnt lgkmcnt(3)
	v_mfma_f32_32x32x16_bf16 v[64:79], v[216:219], v[220:223], v[64:79]
	ds_read_b128 v[96:99], v192 offset:3072
	ds_read_b128 v[212:215], v233 offset:33024
	ds_read_b128 v[216:219], v233 offset:45312
	v_mfma_f32_32x32x16_bf16 v[80:95], v[124:127], v[220:223], v[80:95]
	v_cvt_pk_bf16_f32 v104, v104, v105
	v_cvt_pk_bf16_f32 v105, v106, v107
	v_cvt_pk_bf16_f32 v106, v108, v109
	v_cvt_pk_bf16_f32 v107, v110, v111
	s_nop 0
	v_permlane32_swap_b32_e32 v104, v106
	v_permlane32_swap_b32_e32 v105, v107
	s_cmp_lt_u32 s69, 0x1000
	s_cbranch_scc1 .Lattn_dBy4
	s_mov_b32 m0, s71
	s_nop 0
	buffer_load_dwordx4 v198, s[28:31], s51 offen lds
.Lattn_dBy4:
	s_waitcnt lgkmcnt(3)
	v_mfma_f32_32x32x16_bf16 v[64:79], v[208:211], v[224:227], v[64:79]
	v_mfma_f32_32x32x16_bf16 v[80:95], v[118:121], v[224:227], v[80:95]
	v_cvt_pk_bf16_f32 v100, v229, v230
	v_cvt_pk_bf16_f32 v101, v231, v232
	v_cvt_pk_bf16_f32 v102, v234, v235
	v_cvt_pk_bf16_f32 v103, v236, v237
	s_nop 0
	v_permlane32_swap_b32_e32 v100, v102
	v_permlane32_swap_b32_e32 v101, v103
	s_waitcnt lgkmcnt(1)
	v_mfma_f32_32x32x16_bf16 v[64:79], v[212:215], v[96:99], v[64:79]
	s_waitcnt lgkmcnt(0)
	v_mfma_f32_32x32x16_bf16 v[80:95], v[216:219], v[96:99], v[80:95]
	v_cvt_pk_bf16_f32 v96, v238, v239
	v_cvt_pk_bf16_f32 v97, v240, v241
	v_cvt_pk_bf16_f32 v98, v242, v243
	v_cvt_pk_bf16_f32 v99, v244, v245
	s_nop 0
	v_permlane32_swap_b32_e32 v96, v98
	v_permlane32_swap_b32_e32 v97, v99
	ds_read_b64_tr_b16 v[110:111], v188 offset:18432
	ds_read_b64_tr_b16 v[108:109], v188 offset:16384
	ds_read_b64_tr_b16 v[118:119], v188 offset:16896
	ds_read_b64_tr_b16 v[122:123], v188 offset:17408
	ds_read_b64_tr_b16 v[208:209], v188 offset:17920
	ds_read_b64_tr_b16 v[120:121], v188 offset:18944
	ds_read_b64_tr_b16 v[124:125], v188 offset:19456
	ds_read_b64_tr_b16 v[210:211], v188 offset:19968
	s_waitcnt lgkmcnt(6)
	v_mfma_f32_32x32x16_bf16 v[0:15], v[112:115], v[108:111], v[0:15]
	s_waitcnt lgkmcnt(2)
	v_mfma_f32_32x32x16_bf16 v[48:63], v[112:115], v[118:121], v[48:63]
	v_max_f32_e32 v108, v65, v65
	v_max_f32_e32 v109, v64, v64
	v_max_f32_e32 v108, v109, v108
	v_max3_f32 v108, v108, v66, v67
	v_max3_f32 v108, v108, v68, v69
	v_max3_f32 v108, v108, v70, v71
	v_max3_f32 v108, v108, v72, v73
	v_max3_f32 v108, v108, v74, v75
	v_max3_f32 v108, v108, v76, v77
	v_max3_f32 v118, v108, v78, v79
	s_waitcnt lgkmcnt(1)
	v_mfma_f32_32x32x16_bf16 v[32:47], v[112:115], v[122:125], v[32:47]
	ds_read_b64_tr_b16 v[108:109], v188 offset:20480
	ds_read_b64_tr_b16 v[110:111], v188 offset:22528
	ds_read_b64_tr_b16 v[122:123], v188 offset:23040
	ds_read_b64_tr_b16 v[120:121], v188 offset:20992
	s_waitcnt lgkmcnt(4)
	v_mfma_f32_32x32x16_bf16 v[16:31], v[112:115], v[208:211], v[16:31]
	v_max3_f32 v112, v118, v80, v81
	v_max3_f32 v112, v112, v82, v83
	v_max3_f32 v112, v112, v84, v85
	v_max3_f32 v112, v112, v86, v87
	v_max3_f32 v112, v112, v88, v89
	v_max3_f32 v112, v112, v90, v91
	v_max3_f32 v112, v112, v92, v93
	v_max3_f32 v112, v112, v94, v95
	v_mov_b32_e32 v113, v112
	s_nop 1
	v_permlane32_swap_b32_e32 v112, v113
	v_max_f32_e32 v113, v113, v113
	v_max_f32_e32 v112, v112, v112
	v_max_f32_e32 v118, v112, v113
	s_waitcnt lgkmcnt(2)
	v_mfma_f32_32x32x16_bf16 v[0:15], v[104:107], v[108:111], v[0:15]
	ds_read_b64_tr_b16 v[112:113], v188 offset:21504
	ds_read_b64_tr_b16 v[114:115], v188 offset:23552
	ds_read_b64_tr_b16 v[110:111], v188 offset:24064
	ds_read_b64_tr_b16 v[108:109], v188 offset:22016
	s_waitcnt lgkmcnt(4)
	v_mfma_f32_32x32x16_bf16 v[48:63], v[104:107], v[120:123], v[48:63]
	v_cmp_ge_f32_e32 vcc, s67, v118
	s_cmp_eq_u64 vcc, exec
	v_mov_b32_e32 v205, 1.0
	s_cbranch_scc0 .LBB0_669
